# waitcnt placement: QKV value-tile epilogue no longer waits vmcnt(0) (no gains loaded on that path; wait only covered next-tile prefetch)
# speedup vs baseline: 1.0088x; 1.0023x over previous
;     __device__ __forceinline__ void operator()(AccT& acc, const Unit& u, int wr, int wc, int fr, int fq, PG8_LAS unsigned char* lds) const {
;     ...
; #pragma unroll
;         for (int ai = 0; ai < 2; ++ai)
; #pragma unroll
;             for (int m = 0; m < 4; ++m) { bf16_t* rowp = out + (size_t)(rowbase + ai * HALF + m * 16) * ldc + col0;
; #pragma unroll
;                 for (int bj = 0; bj < 2; ++bj) { const float r = normed ? rn[ai][m][NSEG == 1 ? 0 : bj] : rs[ai][m];
.LBB0_766:
	s_waitcnt lgkmcnt(0)
	v_mov_b32_e32 v176, v157
	v_mov_b32_e32 v174, v159
	v_mov_b32_e32 v170, v161
	v_mov_b32_e32 v166, v163
	v_mov_b64_e32 v[164:165], v[162:163]
	v_mov_b64_e32 v[168:169], v[160:161]
	v_mov_b64_e32 v[172:173], v[158:159]
	v_mov_b64_e32 v[178:179], v[156:157]
	v_lshl_or_b32 v182, s61, 8, v189
	v_lshl_add_u32 v196, s18, 8, v184
	v_ashrrev_i32_e32 v183, 31, v182
	v_mov_b64_e32 v[180:181], s[10:11]
	s_movk_i32 s2, 0x1800
	v_mad_i64_i32 v[192:193], s[0:1], v196, s2, v[180:181]
	v_lshlrev_b64 v[182:183], 1, v[182:183]
	s_branch .Lqkv_final_nowait

; __device__ __forceinline__ unsigned cvt_pk_bf16(float lo, float hi) { unsigned r; asm volatile("v_cvt_pk_bf16_f32 %0, %1, %2" : "=v"(r) : "v"(lo), "v"(hi)); return r; }
;     __device__ __forceinline__ void operator()(AccT& acc, const Unit& u, int wr, int wc, int fr, int fq, PG8_LAS unsigned char* lds) const {
;     ...
; #pragma unroll
;         for (int ai = 0; ai < 2; ++ai)
; #pragma unroll
;             for (int m = 0; m < 4; ++m) { bf16_t* rowp = out + (size_t)(rowbase + ai * HALF + m * 16) * ldc + col0;
; #pragma unroll
;                 for (int bj = 0; bj < 2; ++bj) { const float r = normed ? rn[ai][m][NSEG == 1 ? 0 : bj] : rs[ai][m];
;                     const f32x4 v0 = acc[ai][bj][m][0] * gv[bj][0] * r, v1 = acc[ai][bj][m][1] * gv[bj][1] * r;
;                     u32x4 w; w.x = cvt_pk_bf16(v0[0], v0[1]); w.y = cvt_pk_bf16(v0[2], v0[3]); w.z = cvt_pk_bf16(v1[0], v1[1]); w.w = cvt_pk_bf16(v1[2], v1[3]);
;                     *(u32x4*)(rowp + bj * HALF) = w; } }
.Lqkv_final_nowait:
	v_pk_mul_f32 v[126:127], v[126:127], v[134:135]
	v_pk_mul_f32 v[124:125], v[124:125], v[132:133]
	v_pk_mul_f32 v[122:123], v[122:123], v[130:131]
	v_pk_mul_f32 v[120:121], v[120:121], v[128:129]
	v_lshl_add_u64 v[192:193], v[192:193], 0, v[182:183]
	v_pk_mul_f32 v[126:127], v[126:127], v[164:165] op_sel_hi:[1,0]
	v_pk_mul_f32 v[124:125], v[124:125], v[164:165] op_sel_hi:[1,0]
	v_pk_mul_f32 v[194:195], v[122:123], v[164:165] op_sel_hi:[1,0]
	v_pk_mul_f32 v[122:123], v[120:121], v[164:165] op_sel_hi:[1,0]
	v_cvt_pk_bf16_f32 v120, v124, v125
	v_cvt_pk_bf16_f32 v121, v126, v127
	v_pk_mul_f32 v[116:117], v[116:117], v[140:141]
	v_pk_mul_f32 v[110:111], v[110:111], v[138:139]
	v_pk_mul_f32 v[108:109], v[108:109], v[136:137]
	v_cvt_pk_bf16_f32 v122, v122, v123
	v_cvt_pk_bf16_f32 v123, v194, v195
	global_store_dwordx4 v[192:193], v[120:123], off
	v_pk_mul_f32 v[118:119], v[118:119], v[142:143]
	v_pk_mul_f32 v[116:117], v[116:117], v[162:163] op_sel_hi:[1,0]
	v_pk_mul_f32 v[120:121], v[110:111], v[162:163] op_sel_hi:[1,0]
	v_pk_mul_f32 v[110:111], v[108:109], v[162:163] op_sel_hi:[1,0]
	v_cvt_pk_bf16_f32 v108, v116, v117
	v_pk_mul_f32 v[118:119], v[118:119], v[162:163] op_sel_hi:[1,0]
	v_pk_mul_f32 v[112:113], v[112:113], v[132:133]
	v_cvt_pk_bf16_f32 v109, v118, v119
	v_cvt_pk_bf16_f32 v110, v110, v111
	v_cvt_pk_bf16_f32 v111, v120, v121
	global_store_dwordx4 v[192:193], v[108:111], off offset:256
	v_pk_mul_f32 v[106:107], v[106:107], v[130:131]
	v_pk_mul_f32 v[104:105], v[104:105], v[128:129]
	v_or_b32_e32 v108, 16, v196
	v_mad_i64_i32 v[108:109], s[0:1], v108, s2, v[180:181]
	v_lshl_add_u64 v[108:109], v[108:109], 0, v[182:183]
	v_pk_mul_f32 v[110:111], v[114:115], v[134:135]
	v_pk_mul_f32 v[112:113], v[112:113], v[166:167] op_sel_hi:[1,0]
	v_pk_mul_f32 v[114:115], v[106:107], v[166:167] op_sel_hi:[1,0]
	v_pk_mul_f32 v[106:107], v[104:105], v[166:167] op_sel_hi:[1,0]
	v_cvt_pk_bf16_f32 v104, v112, v113
	v_pk_mul_f32 v[110:111], v[110:111], v[166:167] op_sel_hi:[1,0]
	v_pk_mul_f32 v[100:101], v[100:101], v[140:141]
	v_cvt_pk_bf16_f32 v105, v110, v111
	v_cvt_pk_bf16_f32 v106, v106, v107
	v_cvt_pk_bf16_f32 v107, v114, v115
	global_store_dwordx4 v[108:109], v[104:107], off
	v_pk_mul_f32 v[94:95], v[94:95], v[138:139]
	v_pk_mul_f32 v[92:93], v[92:93], v[136:137]
	v_mov_b32_e32 v104, v163
	v_pk_mul_f32 v[102:103], v[102:103], v[142:143]
	v_pk_mul_f32 v[100:101], v[100:101], v[104:105] op_sel_hi:[1,0]
	v_pk_mul_f32 v[106:107], v[94:95], v[104:105] op_sel_hi:[1,0]
	v_pk_mul_f32 v[94:95], v[92:93], v[104:105] op_sel_hi:[1,0]
	v_cvt_pk_bf16_f32 v92, v100, v101
	v_pk_mul_f32 v[102:103], v[102:103], v[104:105] op_sel_hi:[1,0]
	v_pk_mul_f32 v[96:97], v[96:97], v[132:133]
	v_cvt_pk_bf16_f32 v93, v102, v103
	v_cvt_pk_bf16_f32 v94, v94, v95
	v_cvt_pk_bf16_f32 v95, v106, v107
	global_store_dwordx4 v[108:109], v[92:95], off offset:256
	v_pk_mul_f32 v[90:91], v[90:91], v[130:131]
	v_pk_mul_f32 v[88:89], v[88:89], v[128:129]
	v_or_b32_e32 v92, 32, v196
	v_mad_i64_i32 v[92:93], s[0:1], v92, s2, v[180:181]
	v_pk_mul_f32 v[94:95], v[98:99], v[134:135]
	v_lshl_add_u64 v[92:93], v[92:93], 0, v[182:183]
	v_pk_mul_f32 v[94:95], v[94:95], v[168:169] op_sel_hi:[1,0]
	v_pk_mul_f32 v[96:97], v[96:97], v[168:169] op_sel_hi:[1,0]
	v_pk_mul_f32 v[98:99], v[90:91], v[168:169] op_sel_hi:[1,0]
	v_pk_mul_f32 v[90:91], v[88:89], v[168:169] op_sel_hi:[1,0]
	v_cvt_pk_bf16_f32 v88, v96, v97
	v_cvt_pk_bf16_f32 v89, v94, v95
	v_pk_mul_f32 v[84:85], v[84:85], v[140:141]
	v_pk_mul_f32 v[78:79], v[78:79], v[138:139]
	v_pk_mul_f32 v[76:77], v[76:77], v[136:137]
	v_cvt_pk_bf16_f32 v90, v90, v91
	v_cvt_pk_bf16_f32 v91, v98, v99
	global_store_dwordx4 v[92:93], v[88:91], off
	v_pk_mul_f32 v[86:87], v[86:87], v[142:143]
	v_pk_mul_f32 v[84:85], v[84:85], v[160:161] op_sel_hi:[1,0]
	v_pk_mul_f32 v[88:89], v[78:79], v[160:161] op_sel_hi:[1,0]
	v_pk_mul_f32 v[78:79], v[76:77], v[160:161] op_sel_hi:[1,0]
	v_cvt_pk_bf16_f32 v76, v84, v85
	v_pk_mul_f32 v[86:87], v[86:87], v[160:161] op_sel_hi:[1,0]
	v_pk_mul_f32 v[80:81], v[80:81], v[132:133]
	v_cvt_pk_bf16_f32 v77, v86, v87
	v_cvt_pk_bf16_f32 v78, v78, v79
	v_cvt_pk_bf16_f32 v79, v88, v89
	global_store_dwordx4 v[92:93], v[76:79], off offset:256
	v_pk_mul_f32 v[74:75], v[74:75], v[130:131]
	v_pk_mul_f32 v[72:73], v[72:73], v[128:129]
	v_or_b32_e32 v76, 48, v196
	v_mad_i64_i32 v[76:77], s[0:1], v76, s2, v[180:181]
	v_lshl_add_u64 v[76:77], v[76:77], 0, v[182:183]
	v_pk_mul_f32 v[78:79], v[82:83], v[134:135]
	v_pk_mul_f32 v[80:81], v[80:81], v[170:171] op_sel_hi:[1,0]
	v_pk_mul_f32 v[82:83], v[74:75], v[170:171] op_sel_hi:[1,0]
	v_pk_mul_f32 v[74:75], v[72:73], v[170:171] op_sel_hi:[1,0]
	v_cvt_pk_bf16_f32 v72, v80, v81
	v_pk_mul_f32 v[78:79], v[78:79], v[170:171] op_sel_hi:[1,0]
	v_pk_mul_f32 v[68:69], v[68:69], v[140:141]
	v_cvt_pk_bf16_f32 v73, v78, v79
	v_cvt_pk_bf16_f32 v74, v74, v75
	v_cvt_pk_bf16_f32 v75, v82, v83
	global_store_dwordx4 v[76:77], v[72:75], off
	v_pk_mul_f32 v[66:67], v[66:67], v[138:139]
	v_pk_mul_f32 v[64:65], v[64:65], v[136:137]
	v_mov_b32_e32 v72, v161
	v_pk_mul_f32 v[70:71], v[70:71], v[142:143]
	v_pk_mul_f32 v[68:69], v[68:69], v[72:73] op_sel_hi:[1,0]
	v_pk_mul_f32 v[74:75], v[66:67], v[72:73] op_sel_hi:[1,0]
	v_pk_mul_f32 v[66:67], v[64:65], v[72:73] op_sel_hi:[1,0]
	v_cvt_pk_bf16_f32 v64, v68, v69
	v_pk_mul_f32 v[70:71], v[70:71], v[72:73] op_sel_hi:[1,0]
	v_pk_mul_f32 v[62:63], v[62:63], v[134:135]
	v_cvt_pk_bf16_f32 v65, v70, v71
	v_cvt_pk_bf16_f32 v66, v66, v67
	v_cvt_pk_bf16_f32 v67, v74, v75
; __device__ __forceinline__ unsigned cvt_pk_bf16(float lo, float hi) { unsigned r; asm volatile("v_cvt_pk_bf16_f32 %0, %1, %2" : "=v"(r) : "v"(lo), "v"(hi)); return r; }
; #define PG8_BAR __builtin_amdgcn_s_barrier()
;     __device__ __forceinline__ void operator()(AccT& acc, const Unit& u, int wr, int wc, int fr, int fq, PG8_LAS unsigned char* lds) const {
;     ...
;             for (int m = 0; m < 4; ++m) { bf16_t* rowp = out + (size_t)(rowbase + ai * HALF + m * 16) * ldc + col0;
; #pragma unroll
;                 for (int bj = 0; bj < 2; ++bj) { const float r = normed ? rn[ai][m][NSEG == 1 ? 0 : bj] : rs[ai][m];
;                     const f32x4 v0 = acc[ai][bj][m][0] * gv[bj][0] * r, v1 = acc[ai][bj][m][1] * gv[bj][1] * r;
;                     u32x4 w; w.x = cvt_pk_bf16(v0[0], v0[1]); w.y = cvt_pk_bf16(v0[2], v0[3]); w.z = cvt_pk_bf16(v1[0], v1[1]); w.w = cvt_pk_bf16(v1[2], v1[3]);
;                     *(u32x4*)(rowp + bj * HALF) = w; } }
;     ...
;         if (wr == 1) PG8_BAR;
	global_store_dwordx4 v[76:77], v[64:67], off offset:256
	v_pk_mul_f32 v[60:61], v[60:61], v[132:133]
	v_pk_mul_f32 v[58:59], v[58:59], v[130:131]
	v_add_u32_e32 v64, 0x80, v196
	v_mad_i64_i32 v[64:65], s[0:1], v64, s2, v[180:181]
	v_pk_mul_f32 v[56:57], v[56:57], v[128:129]
	v_lshl_add_u64 v[64:65], v[64:65], 0, v[182:183]
	v_pk_mul_f32 v[62:63], v[62:63], v[172:173] op_sel_hi:[1,0]
	v_pk_mul_f32 v[60:61], v[60:61], v[172:173] op_sel_hi:[1,0]
	v_pk_mul_f32 v[66:67], v[58:59], v[172:173] op_sel_hi:[1,0]
	v_pk_mul_f32 v[58:59], v[56:57], v[172:173] op_sel_hi:[1,0]
	v_cvt_pk_bf16_f32 v56, v60, v61
	v_cvt_pk_bf16_f32 v57, v62, v63
	v_pk_mul_f32 v[52:53], v[52:53], v[140:141]
	v_pk_mul_f32 v[46:47], v[46:47], v[138:139]
	v_pk_mul_f32 v[44:45], v[44:45], v[136:137]
	v_cvt_pk_bf16_f32 v58, v58, v59
	v_cvt_pk_bf16_f32 v59, v66, v67
	global_store_dwordx4 v[64:65], v[56:59], off
	v_pk_mul_f32 v[54:55], v[54:55], v[142:143]
	v_pk_mul_f32 v[52:53], v[52:53], v[158:159] op_sel_hi:[1,0]
	v_pk_mul_f32 v[56:57], v[46:47], v[158:159] op_sel_hi:[1,0]
	v_pk_mul_f32 v[46:47], v[44:45], v[158:159] op_sel_hi:[1,0]
	v_cvt_pk_bf16_f32 v44, v52, v53
	v_pk_mul_f32 v[54:55], v[54:55], v[158:159] op_sel_hi:[1,0]
	v_pk_mul_f32 v[48:49], v[48:49], v[132:133]
	v_cvt_pk_bf16_f32 v45, v54, v55
	v_cvt_pk_bf16_f32 v46, v46, v47
	v_cvt_pk_bf16_f32 v47, v56, v57
	global_store_dwordx4 v[64:65], v[44:47], off offset:256
	v_pk_mul_f32 v[42:43], v[42:43], v[130:131]
	v_pk_mul_f32 v[40:41], v[40:41], v[128:129]
	v_add_u32_e32 v44, 0x90, v196
	v_mad_i64_i32 v[44:45], s[0:1], v44, s2, v[180:181]
	v_lshl_add_u64 v[44:45], v[44:45], 0, v[182:183]
	v_pk_mul_f32 v[46:47], v[50:51], v[134:135]
	v_pk_mul_f32 v[48:49], v[48:49], v[174:175] op_sel_hi:[1,0]
	v_pk_mul_f32 v[50:51], v[42:43], v[174:175] op_sel_hi:[1,0]
	v_pk_mul_f32 v[42:43], v[40:41], v[174:175] op_sel_hi:[1,0]
	v_cvt_pk_bf16_f32 v40, v48, v49
	v_pk_mul_f32 v[46:47], v[46:47], v[174:175] op_sel_hi:[1,0]
	v_pk_mul_f32 v[36:37], v[36:37], v[140:141]
	v_cvt_pk_bf16_f32 v41, v46, v47
	v_cvt_pk_bf16_f32 v42, v42, v43
	v_cvt_pk_bf16_f32 v43, v50, v51
	global_store_dwordx4 v[44:45], v[40:43], off
	v_pk_mul_f32 v[30:31], v[30:31], v[138:139]
	v_pk_mul_f32 v[28:29], v[28:29], v[136:137]
	v_mov_b32_e32 v40, v159
	v_pk_mul_f32 v[38:39], v[38:39], v[142:143]
	v_pk_mul_f32 v[36:37], v[36:37], v[40:41] op_sel_hi:[1,0]
	v_pk_mul_f32 v[42:43], v[30:31], v[40:41] op_sel_hi:[1,0]
	v_pk_mul_f32 v[30:31], v[28:29], v[40:41] op_sel_hi:[1,0]
	v_cvt_pk_bf16_f32 v28, v36, v37
	v_pk_mul_f32 v[38:39], v[38:39], v[40:41] op_sel_hi:[1,0]
	v_pk_mul_f32 v[32:33], v[32:33], v[132:133]
	v_cvt_pk_bf16_f32 v29, v38, v39
	v_cvt_pk_bf16_f32 v30, v30, v31
	v_cvt_pk_bf16_f32 v31, v42, v43
	global_store_dwordx4 v[44:45], v[28:31], off offset:256
	v_pk_mul_f32 v[26:27], v[26:27], v[130:131]
	v_pk_mul_f32 v[24:25], v[24:25], v[128:129]
	v_add_u32_e32 v28, 0xa0, v196
	v_mad_i64_i32 v[28:29], s[0:1], v28, s2, v[180:181]
	v_pk_mul_f32 v[30:31], v[34:35], v[134:135]
	v_lshl_add_u64 v[28:29], v[28:29], 0, v[182:183]
	v_pk_mul_f32 v[30:31], v[30:31], v[178:179] op_sel_hi:[1,0]
	v_pk_mul_f32 v[32:33], v[32:33], v[178:179] op_sel_hi:[1,0]
	v_pk_mul_f32 v[34:35], v[26:27], v[178:179] op_sel_hi:[1,0]
	v_pk_mul_f32 v[26:27], v[24:25], v[178:179] op_sel_hi:[1,0]
	v_cvt_pk_bf16_f32 v24, v32, v33
	v_cvt_pk_bf16_f32 v25, v30, v31
	v_pk_mul_f32 v[20:21], v[20:21], v[140:141]
	v_pk_mul_f32 v[14:15], v[14:15], v[138:139]
	v_pk_mul_f32 v[12:13], v[12:13], v[136:137]
	v_cvt_pk_bf16_f32 v26, v26, v27
	v_cvt_pk_bf16_f32 v27, v34, v35
	global_store_dwordx4 v[28:29], v[24:27], off
	v_pk_mul_f32 v[22:23], v[22:23], v[142:143]
	v_pk_mul_f32 v[20:21], v[20:21], v[156:157] op_sel_hi:[1,0]
	v_pk_mul_f32 v[24:25], v[14:15], v[156:157] op_sel_hi:[1,0]
	v_pk_mul_f32 v[14:15], v[12:13], v[156:157] op_sel_hi:[1,0]
	v_cvt_pk_bf16_f32 v12, v20, v21
	v_pk_mul_f32 v[22:23], v[22:23], v[156:157] op_sel_hi:[1,0]
	v_pk_mul_f32 v[16:17], v[16:17], v[132:133]
	v_cvt_pk_bf16_f32 v13, v22, v23
	v_cvt_pk_bf16_f32 v14, v14, v15
	v_cvt_pk_bf16_f32 v15, v24, v25
	global_store_dwordx4 v[28:29], v[12:15], off offset:256
	v_pk_mul_f32 v[10:11], v[10:11], v[130:131]
	v_pk_mul_f32 v[8:9], v[8:9], v[128:129]
	v_add_u32_e32 v12, 0xb0, v196
	v_mad_i64_i32 v[12:13], s[0:1], v12, s2, v[180:181]
	v_lshl_add_u64 v[12:13], v[12:13], 0, v[182:183]
	v_pk_mul_f32 v[14:15], v[18:19], v[134:135]
	v_pk_mul_f32 v[16:17], v[16:17], v[176:177] op_sel_hi:[1,0]
	v_pk_mul_f32 v[18:19], v[10:11], v[176:177] op_sel_hi:[1,0]
	v_pk_mul_f32 v[10:11], v[8:9], v[176:177] op_sel_hi:[1,0]
	v_cvt_pk_bf16_f32 v8, v16, v17
	v_pk_mul_f32 v[14:15], v[14:15], v[176:177] op_sel_hi:[1,0]
	v_pk_mul_f32 v[2:3], v[2:3], v[138:139]
	v_cvt_pk_bf16_f32 v9, v14, v15
	v_cvt_pk_bf16_f32 v10, v10, v11
	v_cvt_pk_bf16_f32 v11, v18, v19
	global_store_dwordx4 v[12:13], v[8:11], off
	v_pk_mul_f32 v[0:1], v[0:1], v[136:137]
	v_pk_mul_f32 v[6:7], v[6:7], v[142:143]
	v_mov_b32_e32 v8, v157
	v_pk_mul_f32 v[4:5], v[4:5], v[140:141]
	v_pk_mul_f32 v[10:11], v[2:3], v[8:9] op_sel_hi:[1,0]
	v_pk_mul_f32 v[2:3], v[0:1], v[8:9] op_sel_hi:[1,0]
	s_andn2_b64 vcc, exec, s[38:39]
	s_mov_b64 s[0:1], -1
	v_pk_mul_f32 v[6:7], v[6:7], v[8:9] op_sel_hi:[1,0]
	v_pk_mul_f32 v[4:5], v[4:5], v[8:9] op_sel_hi:[1,0]
	s_nop 0
	v_cvt_pk_bf16_f32 v0, v4, v5
	v_cvt_pk_bf16_f32 v1, v6, v7
	v_cvt_pk_bf16_f32 v2, v2, v3
	v_cvt_pk_bf16_f32 v3, v10, v11
	global_store_dwordx4 v[12:13], v[0:3], off offset:256
	s_cbranch_vccnz .LBB0_698
	s_andn2_b64 vcc, exec, s[4:5]
	s_cbranch_vccnz .LBB0_697
	s_barrier
	s_branch .LBB0_697
